# P8 GLA scan phase hand-rewritten: every wave keeps full 128x16 state slice, no inter-wave exchange, one barrier per step
# baseline (speedup 1.0000x reference)
.LBB0_906:
	s_cmp_lt_i32 s90, 9
	s_cselect_b64 s[2:3], -1, 0
	s_and_b64 s[38:39], s[2:3], s[0:1]
	s_andn2_b64 vcc, exec, s[38:39]
	s_cbranch_vccnz .LBB0_998
	s_mov_b64 s[70:71], s[62:63]
	s_mov_b32 s68, s59
	s_mov_b64 s[66:67], s[60:61]
	s_cmpk_gt_i32 s58, 0xff
	v_readfirstlane_b32 s20, v0
	s_cbranch_scc1 .LBB0_997
	v_readlane_b32 s15, v251, 48
	v_readfirstlane_b32 s35, v0
	s_lshr_b32 s35, s35, 6
	s_and_b32 s36, s35, 3
	s_lshr_b32 s37, s35, 2
	s_and_b32 s31, s15, 1
	s_bfe_u32 s73, s15, 0x20001
	s_bfe_u32 s74, s15, 0x20003
	s_lshr_b32 s72, s15, 5
	s_lshl_b32 s33, s72, 8
	s_addk_i32 s33, 0x4000
	s_lshl_b32 s34, s72, 11
	s_addk_i32 s34, 0xff00
	s_movk_i32 s48, 0x1800
	s_movk_i32 s49, 0x400
	s_cmp_eq_u32 s31, 0
	s_cselect_b32 s30, s48, s49
	s_lshl_b32 s48, s73, 8
	s_add_u32 s49, s88, 0xa27d000
	s_addc_u32 s52, s89, 0
	s_cmp_eq_u32 s31, 0
	s_cselect_b32 s16, s96, s49
	s_cselect_b32 s17, s97, s52
	s_add_u32 s16, s16, s48
	s_addc_u32 s17, s17, 0
	s_add_u32 s49, s88, 0xb27d000
	s_addc_u32 s52, s89, 0
	s_add_u32 s53, s96, 0x400
	s_addc_u32 s64, s97, 0
	s_cmp_eq_u32 s31, 0
	s_cselect_b32 s18, s53, s49
	s_cselect_b32 s19, s64, s52
	s_add_u32 s18, s18, s48
	s_addc_u32 s19, s19, 0
	s_lshl_b32 s49, s73, 9
	s_lshl_b32 s52, s74, 7
	s_add_i32 s49, s49, s52
	s_add_i32 s52, s49, 0x800
	s_add_u32 s20, s96, s52
	s_addc_u32 s21, s97, 0
	v_readlane_b32 s28, v251, 34
	v_readlane_b32 s29, v251, 35
	s_lshl_b32 s52, s31, 25
	s_add_i32 s52, s52, s49
	s_add_u32 s28, s28, s52
	s_addc_u32 s29, s29, 0
	s_lshl_b32 s49, s31, 3
	s_add_i32 s49, s49, s72
	s_lshl_b32 s49, s49, 2
	s_add_i32 s49, s49, s73
	s_mul_i32 s49, s49, 0x4800
	s_add_u32 s22, s88, 0x115d000
	s_addc_u32 s23, s89, 0
	s_add_u32 s22, s22, s49
	s_addc_u32 s23, s23, 0
	v_bfe_u32 v94, v0, 4, 2
	v_lshrrev_b32_e32 v95, 2, v186
	v_and_b32_e32 v96, 3, v186
	v_mov_b32_e32 v97, 0x110
	v_mul_u32_u24_e32 v98, v186, v97
	v_lshl_add_u32 v242, v94, 4, v98
	v_lshl_add_u32 v243, v94, 3, v98
	v_lshl_add_u32 v99, v94, 2, v95
	v_mul_u32_u24_e32 v245, v99, v97
	v_lshl_add_u32 v245, v96, 3, v245
	v_mov_b32_e32 v97, 0x90
	v_mul_u32_u24_e32 v244, v99, v97
	v_lshl_add_u32 v244, v96, 3, v244
	s_lshl_b32 s49, s36, 5
	v_add_u32_e32 v244, s49, v244
	v_lshlrev_b32_e32 v246, 4, v94
	v_add_u32_e32 v246, 0x15800, v246
	v_lshrrev_b32_e32 v95, 4, v0
	v_mov_b32_e32 v97, 0x110
	v_mul_u32_u24_e32 v247, v95, v97
	v_lshl_add_u32 v247, v186, 4, v247
	v_lshrrev_b32_e32 v96, 3, v0
	v_and_b32_e32 v98, 7, v0
	v_mov_b32_e32 v97, 0x90
	v_mul_u32_u24_e32 v248, v96, v97
	v_lshl_add_u32 v248, v98, 4, v248
	v_lshlrev_b32_e32 v240, 2, v0
	v_add_u32_e32 v249, 0x15800, v240
	s_cmp_eq_u32 s31, 0
	s_cselect_b64 vcc, -1, 0
	v_sub_u32_e32 v99, 63, v95
	v_cndmask_b32_e32 v99, v99, v95, vcc
	v_mul_lo_u32 v237, v99, s30
	v_lshl_add_u32 v237, v186, 4, v237
	v_add_u32_e32 v95, 32, v95
	v_sub_u32_e32 v99, 63, v95
	v_cndmask_b32_e32 v99, v99, v95, vcc
	v_mul_lo_u32 v238, v99, s30
	v_lshl_add_u32 v238, v186, 4, v238
	v_sub_u32_e32 v99, 63, v96
	v_cndmask_b32_e32 v99, v99, v96, vcc
	v_mov_b32_e32 v97, 0x1800
	v_mul_lo_u32 v239, v99, v97
	v_lshl_add_u32 v239, v98, 4, v239
	v_sub_u32_e32 v99, 15, v186
	v_cndmask_b32_e32 v99, v99, v186, vcc
	v_lshlrev_b32_e32 v241, 11, v99
	v_lshl_add_u32 v241, v94, 3, v241
	v_add_u32_e32 v241, s49, v241
	v_lshlrev_b32_e32 v95, 2, v94
	v_cmp_gt_u32_e64 s[40:41], v95, v186
	v_add_u32_e32 v96, 1, v95
	v_cmp_gt_u32_e64 s[42:43], v96, v186
	v_add_u32_e32 v96, 2, v95
	v_cmp_gt_u32_e64 s[44:45], v96, v186
	v_add_u32_e32 v96, 3, v95
	v_cmp_gt_u32_e64 s[46:47], v96, v186
	v_mov_b32_e32 v2, 0
	v_mov_b32_e32 v3, 0
	v_mov_b32_e32 v4, 0
	v_mov_b32_e32 v5, 0
	v_mov_b32_e32 v6, 0
	v_mov_b32_e32 v7, 0
	v_mov_b32_e32 v8, 0
	v_mov_b32_e32 v9, 0
	v_mov_b32_e32 v10, 0
	v_mov_b32_e32 v11, 0
	v_mov_b32_e32 v12, 0
	v_mov_b32_e32 v13, 0
	v_mov_b32_e32 v14, 0
	v_mov_b32_e32 v15, 0
	v_mov_b32_e32 v16, 0
	v_mov_b32_e32 v17, 0
	v_mov_b32_e32 v18, 0
	v_mov_b32_e32 v19, 0
	v_mov_b32_e32 v20, 0
	v_mov_b32_e32 v21, 0
	v_mov_b32_e32 v22, 0
	v_mov_b32_e32 v23, 0
	v_mov_b32_e32 v24, 0
	v_mov_b32_e32 v25, 0
	v_mov_b32_e32 v26, 0
	v_mov_b32_e32 v27, 0
	v_mov_b32_e32 v28, 0
	v_mov_b32_e32 v29, 0
	v_mov_b32_e32 v30, 0
	v_mov_b32_e32 v31, 0
	v_mov_b32_e32 v32, 0
	v_mov_b32_e32 v33, 0
	v_mov_b32_e32 v134, 0
	v_mov_b32_e32 v135, 0
	v_mov_b32_e32 v136, 0
	v_mov_b32_e32 v137, 0
	v_mov_b32_e32 v138, 0
	v_mov_b32_e32 v139, 0
	v_mov_b32_e32 v140, 0
	v_mov_b32_e32 v141, 0
	v_mov_b32_e32 v142, 0
	v_mov_b32_e32 v143, 0
	v_mov_b32_e32 v144, 0
	v_mov_b32_e32 v145, 0
	v_mov_b32_e32 v146, 0
	v_mov_b32_e32 v147, 0
	v_mov_b32_e32 v148, 0
	v_mov_b32_e32 v149, 0
	s_mov_b32 s12, 0
	s_mov_b32 s64, 0
	s_sub_i32 s48, 3, s64
	s_sub_i32 s49, 39, s64
	s_cmp_lt_u32 s64, 4
	s_cselect_b32 s48, s48, s49
	s_cmp_eq_u32 s31, 0
	s_cselect_b32 s54, s64, s48
	s_lshl_b32 s48, s54, 6
	s_add_i32 s49, s33, s48
	s_add_i32 s48, s34, s48
	s_cmp_lt_u32 s54, 4
	s_cselect_b32 s55, s49, s48
	s_mul_i32 s48, s55, s30
	s_add_u32 s0, s16, s48
	s_addc_u32 s1, s17, 0
	s_add_u32 s2, s18, s48
	s_addc_u32 s3, s19, 0
	s_mul_i32 s48, s55, 0x1800
	s_add_u32 s4, s20, s48
	s_addc_u32 s5, s21, 0
	s_lshl_b32 s48, s54, 9
	s_add_u32 s6, s22, s48
	s_addc_u32 s7, s23, 0
	global_load_dwordx4 v[224:227], v237, s[2:3]
	global_load_dwordx4 v[228:231], v238, s[2:3]
	global_load_dwordx4 v[232:235], v239, s[4:5]
	s_cmp_lt_u32 s64, 4
	s_cbranch_scc1 .Lp8_ldq_1
	global_load_dwordx4 v[216:219], v237, s[0:1]
	global_load_dwordx4 v[220:223], v238, s[0:1]
.Lp8_ldq_1:
	s_cmp_gt_u32 s35, 1
	s_cbranch_scc1 .Lp8_ldd_1
	global_load_dword v236, v240, s[6:7]
.Lp8_ldd_1:
	s_mov_b32 s12, 1
	s_and_b32 s48, s12, 1
	s_mul_i32 s13, s48, 0xac00
	s_xor_b32 s49, s48, 1
	s_mul_i32 s14, s49, 0xac00
	s_lshl_b32 s48, s48, 9
	s_lshl_b32 s49, s49, 9
	v_add_u32_e32 v182, s13, v242
	v_add_u32_e32 v183, s13, v243
	v_add_u32_e32 v184, s13, v244
	v_add_u32_e32 v185, s13, v245
	v_add_u32_e32 v188, s48, v246
	v_add_u32_e32 v189, s14, v247
	v_add_u32_e32 v190, s14, v248
	v_add_u32_e32 v191, s49, v249
	s_mov_b32 s64, 0
	s_waitcnt vmcnt(0)
	ds_write_b128 v189, v[224:227] offset:17408
	ds_write_b128 v189, v[228:231] offset:26112
	ds_write_b128 v190, v[232:235] offset:34816
	s_cmp_lt_u32 s64, 4
	s_cbranch_scc1 .Lp8_stq_2
	ds_write_b128 v189, v[216:219]
	ds_write_b128 v189, v[220:223] offset:8704
.Lp8_stq_2:
	s_cmp_gt_u32 s35, 1
	s_cbranch_scc1 .Lp8_std_2
	ds_write_b32 v191, v236
.Lp8_std_2:
	s_mov_b32 s64, 1
	s_sub_i32 s48, 3, s64
	s_sub_i32 s49, 39, s64
	s_cmp_lt_u32 s64, 4
	s_cselect_b32 s48, s48, s49
	s_cmp_eq_u32 s31, 0
	s_cselect_b32 s54, s64, s48
	s_lshl_b32 s48, s54, 6
	s_add_i32 s49, s33, s48
	s_add_i32 s48, s34, s48
	s_cmp_lt_u32 s54, 4
	s_cselect_b32 s55, s49, s48
	s_mul_i32 s48, s55, s30
	s_add_u32 s0, s16, s48
	s_addc_u32 s1, s17, 0
	s_add_u32 s2, s18, s48
	s_addc_u32 s3, s19, 0
	s_mul_i32 s48, s55, 0x1800
	s_add_u32 s4, s20, s48
	s_addc_u32 s5, s21, 0
	s_lshl_b32 s48, s54, 9
	s_add_u32 s6, s22, s48
	s_addc_u32 s7, s23, 0
	global_load_dwordx4 v[224:227], v237, s[2:3]
	global_load_dwordx4 v[228:231], v238, s[2:3]
	global_load_dwordx4 v[232:235], v239, s[4:5]
	s_cmp_lt_u32 s64, 4
	s_cbranch_scc1 .Lp8_ldq_3
	global_load_dwordx4 v[216:219], v237, s[0:1]
	global_load_dwordx4 v[220:223], v238, s[0:1]

.Lp8_ldd_3:
	s_mov_b32 s12, 0
	s_waitcnt lgkmcnt(0)
	s_barrier
.Lp8_step:
	s_and_b32 s48, s12, 1
	s_mul_i32 s13, s48, 0xac00
	s_xor_b32 s49, s48, 1
	s_mul_i32 s14, s49, 0xac00
	s_lshl_b32 s48, s48, 9
	s_lshl_b32 s49, s49, 9
	v_add_u32_e32 v182, s13, v242
	v_add_u32_e32 v183, s13, v243
	v_add_u32_e32 v184, s13, v244
	v_add_u32_e32 v185, s13, v245
	v_add_u32_e32 v188, s48, v246
	v_add_u32_e32 v189, s14, v247
	v_add_u32_e32 v190, s14, v248
	v_add_u32_e32 v191, s49, v249
	s_cmp_lt_u32 s12, 4
	s_nop 0
	s_cbranch_scc0 .Lp8_lat
	ds_read_b64_tr_b16 v[126:127], v184 offset:34816
	ds_read_b64_tr_b16 v[128:129], v184 offset:37120
	ds_read_b64_tr_b16 v[130:131], v184 offset:39424
	ds_read_b64_tr_b16 v[132:133], v184 offset:41728
	ds_read_b64_tr_b16 v[62:63], v185 offset:17408
	ds_read_b64_tr_b16 v[64:65], v185 offset:21760
	ds_read_b64_tr_b16 v[66:67], v185 offset:26112
	ds_read_b64_tr_b16 v[68:69], v185 offset:30464
	ds_read_b64_tr_b16 v[70:71], v185 offset:17440
	ds_read_b64_tr_b16 v[72:73], v185 offset:21792
	ds_read_b64_tr_b16 v[74:75], v185 offset:26144
	ds_read_b64_tr_b16 v[76:77], v185 offset:30496
	ds_read_b64_tr_b16 v[78:79], v185 offset:17472
	ds_read_b64_tr_b16 v[80:81], v185 offset:21824
	ds_read_b64_tr_b16 v[82:83], v185 offset:26176
	ds_read_b64_tr_b16 v[84:85], v185 offset:30528
	ds_read_b64_tr_b16 v[86:87], v185 offset:17504
	ds_read_b64_tr_b16 v[88:89], v185 offset:21856
	ds_read_b64_tr_b16 v[90:91], v185 offset:26208
	ds_read_b64_tr_b16 v[92:93], v185 offset:30560
	ds_read_b64_tr_b16 v[94:95], v185 offset:17536
	ds_read_b64_tr_b16 v[96:97], v185 offset:21888
	ds_read_b64_tr_b16 v[98:99], v185 offset:26240
	ds_read_b64_tr_b16 v[100:101], v185 offset:30592
	ds_read_b64_tr_b16 v[102:103], v185 offset:17568
	ds_read_b64_tr_b16 v[104:105], v185 offset:21920
	ds_read_b64_tr_b16 v[106:107], v185 offset:26272
	ds_read_b64_tr_b16 v[108:109], v185 offset:30624
	ds_read_b64_tr_b16 v[110:111], v185 offset:17600
	ds_read_b64_tr_b16 v[112:113], v185 offset:21952
	ds_read_b64_tr_b16 v[114:115], v185 offset:26304
	ds_read_b64_tr_b16 v[116:117], v185 offset:30656
	ds_read_b64_tr_b16 v[118:119], v185 offset:17632
	ds_read_b64_tr_b16 v[120:121], v185 offset:21984
	ds_read_b64_tr_b16 v[122:123], v185 offset:26336
	ds_read_b64_tr_b16 v[124:125], v185 offset:30688
	ds_read_b128 v[166:169], v188 offset:0
	ds_read_b128 v[170:173], v188 offset:64
	ds_read_b128 v[174:177], v188 offset:128
	ds_read_b128 v[178:181], v188 offset:192
	ds_read_b128 v[200:203], v188 offset:256
	ds_read_b128 v[204:207], v188 offset:320
	ds_read_b128 v[208:211], v188 offset:384
	ds_read_b128 v[212:215], v188 offset:448
	s_waitcnt lgkmcnt(15)
	v_mfma_f32_16x16x32_bf16 v[2:5], v[62:65], v[126:129], v[2:5]
	v_mfma_f32_16x16x32_bf16 v[2:5], v[66:69], v[130:133], v[2:5]
	s_waitcnt lgkmcnt(15)
	v_mfma_f32_16x16x32_bf16 v[6:9], v[70:73], v[126:129], v[6:9]
	v_mfma_f32_16x16x32_bf16 v[6:9], v[74:77], v[130:133], v[6:9]
	s_waitcnt lgkmcnt(15)
	v_mfma_f32_16x16x32_bf16 v[10:13], v[78:81], v[126:129], v[10:13]
	v_mfma_f32_16x16x32_bf16 v[10:13], v[82:85], v[130:133], v[10:13]
	s_waitcnt lgkmcnt(15)
	v_mfma_f32_16x16x32_bf16 v[14:17], v[86:89], v[126:129], v[14:17]
	v_mfma_f32_16x16x32_bf16 v[14:17], v[90:93], v[130:133], v[14:17]
	s_waitcnt lgkmcnt(15)
	v_mfma_f32_16x16x32_bf16 v[18:21], v[94:97], v[126:129], v[18:21]
	v_mfma_f32_16x16x32_bf16 v[18:21], v[98:101], v[130:133], v[18:21]
	s_waitcnt lgkmcnt(15)
	v_mfma_f32_16x16x32_bf16 v[22:25], v[102:105], v[126:129], v[22:25]
	v_mfma_f32_16x16x32_bf16 v[22:25], v[106:109], v[130:133], v[22:25]
	s_waitcnt lgkmcnt(12)
	v_mfma_f32_16x16x32_bf16 v[26:29], v[110:113], v[126:129], v[26:29]
	v_mfma_f32_16x16x32_bf16 v[26:29], v[114:117], v[130:133], v[26:29]
	s_waitcnt lgkmcnt(8)
	v_mfma_f32_16x16x32_bf16 v[30:33], v[118:121], v[126:129], v[30:33]
	v_mfma_f32_16x16x32_bf16 v[30:33], v[122:125], v[130:133], v[30:33]
	s_add_i32 s64, s12, 1
	s_cmp_gt_u32 s64, 35
	s_nop 5
	s_cbranch_scc1 .Lp8_nost_4
	s_waitcnt vmcnt(0)
	ds_write_b128 v189, v[224:227] offset:17408
	ds_write_b128 v189, v[228:231] offset:26112
	ds_write_b128 v190, v[232:235] offset:34816
	s_cmp_lt_u32 s64, 4
	s_cbranch_scc1 .Lp8_stq_5
	ds_write_b128 v189, v[216:219]
	ds_write_b128 v189, v[220:223] offset:8704

.Lp8_std_5:
	s_add_i32 s64, s12, 2
	s_cmp_gt_u32 s64, 35
	s_cbranch_scc1 .Lp8_nost_4
	s_sub_i32 s48, 3, s64
	s_sub_i32 s49, 39, s64
	s_cmp_lt_u32 s64, 4
	s_cselect_b32 s48, s48, s49
	s_cmp_eq_u32 s31, 0
	s_cselect_b32 s54, s64, s48
	s_lshl_b32 s48, s54, 6
	s_add_i32 s49, s33, s48
	s_add_i32 s48, s34, s48
	s_cmp_lt_u32 s54, 4
	s_cselect_b32 s55, s49, s48
	s_mul_i32 s48, s55, s30
	s_add_u32 s0, s16, s48
	s_addc_u32 s1, s17, 0
	s_add_u32 s2, s18, s48
	s_addc_u32 s3, s19, 0
	s_mul_i32 s48, s55, 0x1800
	s_add_u32 s4, s20, s48
	s_addc_u32 s5, s21, 0
	s_lshl_b32 s48, s54, 9
	s_add_u32 s6, s22, s48
	s_addc_u32 s7, s23, 0
	global_load_dwordx4 v[224:227], v237, s[2:3]
	global_load_dwordx4 v[228:231], v238, s[2:3]
	global_load_dwordx4 v[232:235], v239, s[4:5]
	s_cmp_lt_u32 s64, 4
	s_cbranch_scc1 .Lp8_ldq_6
	global_load_dwordx4 v[216:219], v237, s[0:1]
	global_load_dwordx4 v[220:223], v238, s[0:1]

.Lp8_ldd_6:
.Lp8_nost_4:
	s_waitcnt lgkmcnt(0)
	v_pk_mul_f32 v[2:3], v[2:3], v[166:167]
	v_pk_mul_f32 v[4:5], v[4:5], v[168:169]
	v_pk_mul_f32 v[6:7], v[6:7], v[170:171]
	v_pk_mul_f32 v[8:9], v[8:9], v[172:173]
	v_pk_mul_f32 v[10:11], v[10:11], v[174:175]
	v_pk_mul_f32 v[12:13], v[12:13], v[176:177]
	v_pk_mul_f32 v[14:15], v[14:15], v[178:179]
	v_pk_mul_f32 v[16:17], v[16:17], v[180:181]
	v_pk_mul_f32 v[18:19], v[18:19], v[200:201]
	v_pk_mul_f32 v[20:21], v[20:21], v[202:203]
	v_pk_mul_f32 v[22:23], v[22:23], v[204:205]
	v_pk_mul_f32 v[24:25], v[24:25], v[206:207]
	v_pk_mul_f32 v[26:27], v[26:27], v[208:209]
	v_pk_mul_f32 v[28:29], v[28:29], v[210:211]
	v_pk_mul_f32 v[30:31], v[30:31], v[212:213]
	v_pk_mul_f32 v[32:33], v[32:33], v[214:215]
	s_nop 1
	s_barrier
	s_branch .Lp8_next
.Lp8_lat:
	s_cmp_eq_u32 s37, 0
	s_cbranch_scc0 .Lp8_lat1
	s_sub_i32 s48, 3, s12
	s_sub_i32 s49, 39, s12
	s_cmp_lt_u32 s12, 4
	s_cselect_b32 s48, s48, s49
	s_cmp_eq_u32 s31, 0
	s_cselect_b32 s54, s12, s48
	s_lshl_b32 s48, s54, 6
	s_add_i32 s49, s33, s48
	s_add_i32 s48, s34, s48
	s_cmp_lt_u32 s54, 4
	s_cselect_b32 s55, s49, s48
	s_add_i32 s48, s55, 0
	s_add_i32 s49, s55, 48
	s_cmp_eq_u32 s31, 0
	s_cselect_b32 s48, s48, s49
	s_lshl_b32 s48, s48, 11
	s_add_u32 s8, s28, s48
	s_addc_u32 s9, s29, 0
	s_add_i32 s48, s55, 48
	s_add_i32 s49, s55, 0
	s_cmp_eq_u32 s31, 0
	s_cselect_b32 s48, s48, s49
	s_lshl_b32 s48, s48, 11
	s_add_u32 s10, s28, s48
	s_addc_u32 s11, s29, 0
	ds_read_b64 v[62:63], v183 offset:0
	ds_read_b64 v[64:65], v183 offset:32
	ds_read_b64 v[66:67], v183 offset:64
	ds_read_b64 v[68:69], v183 offset:96
	ds_read_b64 v[70:71], v183 offset:128
	ds_read_b64 v[72:73], v183 offset:160
	ds_read_b64 v[74:75], v183 offset:192
	ds_read_b64 v[76:77], v183 offset:224
	ds_read_b64 v[78:79], v183 offset:13056
	ds_read_b64 v[80:81], v183 offset:13088
	ds_read_b64 v[82:83], v183 offset:13120
	ds_read_b64 v[84:85], v183 offset:13152
	ds_read_b64 v[86:87], v183 offset:13184
	ds_read_b64 v[88:89], v183 offset:13216
	ds_read_b64 v[90:91], v183 offset:13248
	ds_read_b64 v[92:93], v183 offset:13280
	v_cvt_pk_bf16_f32 v150, v2, v3
	v_cvt_pk_bf16_f32 v151, v4, v5
	v_cvt_pk_bf16_f32 v152, v6, v7
	v_cvt_pk_bf16_f32 v153, v8, v9
	v_cvt_pk_bf16_f32 v154, v10, v11
	v_cvt_pk_bf16_f32 v155, v12, v13
	v_cvt_pk_bf16_f32 v156, v14, v15
	v_cvt_pk_bf16_f32 v157, v16, v17
	v_cvt_pk_bf16_f32 v158, v18, v19
	v_cvt_pk_bf16_f32 v159, v20, v21
	v_cvt_pk_bf16_f32 v160, v22, v23
	v_cvt_pk_bf16_f32 v161, v24, v25
	v_cvt_pk_bf16_f32 v162, v26, v27
	v_cvt_pk_bf16_f32 v163, v28, v29
	v_cvt_pk_bf16_f32 v164, v30, v31
	v_cvt_pk_bf16_f32 v165, v32, v33
	ds_read_b64_tr_b16 v[126:127], v184 offset:34816
	ds_read_b64_tr_b16 v[128:129], v184 offset:37120
	ds_read_b64_tr_b16 v[130:131], v184 offset:39424
	ds_read_b64_tr_b16 v[132:133], v184 offset:41728
	ds_read_b128 v[94:97], v182 offset:0
	ds_read_b128 v[98:101], v182 offset:64
	ds_read_b128 v[102:105], v182 offset:128
	ds_read_b128 v[106:109], v182 offset:192
	ds_read_b128 v[110:113], v182 offset:13056
	ds_read_b128 v[114:117], v182 offset:13120
	ds_read_b128 v[118:121], v182 offset:13184
	ds_read_b128 v[122:125], v182 offset:13248
	ds_read_b128 v[166:169], v182 offset:17408
	ds_read_b128 v[170:173], v182 offset:17472
	ds_read_b128 v[174:177], v182 offset:17536
	ds_read_b128 v[178:181], v182 offset:17600
	ds_read_b128 v[200:203], v182 offset:21760
	ds_read_b128 v[204:207], v182 offset:21824
	ds_read_b128 v[208:211], v182 offset:21888
	ds_read_b128 v[212:215], v182 offset:21952
	s_waitcnt lgkmcnt(15)
	v_mfma_f32_16x16x32_bf16 v[34:37], v[150:153], v[62:65], 0
	v_mfma_f32_16x16x32_bf16 v[38:41], v[150:153], v[78:81], 0
	v_mfma_f32_16x16x32_bf16 v[34:37], v[154:157], v[66:69], v[34:37]
	v_mfma_f32_16x16x32_bf16 v[38:41], v[154:157], v[82:85], v[38:41]
	v_mfma_f32_16x16x32_bf16 v[34:37], v[158:161], v[70:73], v[34:37]
	v_mfma_f32_16x16x32_bf16 v[38:41], v[158:161], v[86:89], v[38:41]
	v_mfma_f32_16x16x32_bf16 v[34:37], v[162:165], v[74:77], v[34:37]
	v_mfma_f32_16x16x32_bf16 v[38:41], v[162:165], v[90:93], v[38:41]
	ds_read_b64_tr_b16 v[62:63], v185 offset:17408
	ds_read_b64_tr_b16 v[64:65], v185 offset:21760
	ds_read_b64_tr_b16 v[66:67], v185 offset:26112
	ds_read_b64_tr_b16 v[68:69], v185 offset:30464
	ds_read_b64_tr_b16 v[70:71], v185 offset:17440
	ds_read_b64_tr_b16 v[72:73], v185 offset:21792
	ds_read_b64_tr_b16 v[74:75], v185 offset:26144
	ds_read_b64_tr_b16 v[76:77], v185 offset:30496
	ds_read_b64_tr_b16 v[78:79], v185 offset:17472
	ds_read_b64_tr_b16 v[80:81], v185 offset:21824
	ds_read_b64_tr_b16 v[82:83], v185 offset:26176
	ds_read_b64_tr_b16 v[84:85], v185 offset:30528
	ds_read_b64_tr_b16 v[86:87], v185 offset:17504
	ds_read_b64_tr_b16 v[88:89], v185 offset:21856
	ds_read_b64_tr_b16 v[90:91], v185 offset:26208
	ds_read_b64_tr_b16 v[92:93], v185 offset:30560
	s_waitcnt lgkmcnt(15)
	v_mfma_f32_16x16x32_bf16 v[42:45], v[166:169], v[94:97], 0
	v_mfma_f32_16x16x32_bf16 v[46:49], v[166:169], v[110:113], 0
	v_mfma_f32_16x16x32_bf16 v[42:45], v[170:173], v[98:101], v[42:45]
	v_mfma_f32_16x16x32_bf16 v[46:49], v[170:173], v[114:117], v[46:49]
	v_mfma_f32_16x16x32_bf16 v[42:45], v[174:177], v[102:105], v[42:45]
	v_mfma_f32_16x16x32_bf16 v[46:49], v[174:177], v[118:121], v[46:49]
	v_mfma_f32_16x16x32_bf16 v[42:45], v[178:181], v[106:109], v[42:45]
	v_mfma_f32_16x16x32_bf16 v[46:49], v[178:181], v[122:125], v[46:49]
	ds_read_b128 v[166:169], v182 offset:26112
	ds_read_b128 v[170:173], v182 offset:26176
	ds_read_b128 v[174:177], v182 offset:26240
	ds_read_b128 v[178:181], v182 offset:26304
	v_mfma_f32_16x16x32_bf16 v[50:53], v[200:203], v[110:113], 0
	v_mfma_f32_16x16x32_bf16 v[50:53], v[204:207], v[114:117], v[50:53]
	v_mfma_f32_16x16x32_bf16 v[50:53], v[208:211], v[118:121], v[50:53]
	v_mfma_f32_16x16x32_bf16 v[50:53], v[212:215], v[122:125], v[50:53]
	ds_read_b128 v[200:203], v182 offset:30464
	ds_read_b128 v[204:207], v182 offset:30528
	ds_read_b128 v[208:211], v182 offset:30592
	ds_read_b128 v[212:215], v182 offset:30656
	s_waitcnt lgkmcnt(4)
	v_mfma_f32_16x16x32_bf16 v[54:57], v[166:169], v[110:113], 0
	v_mfma_f32_16x16x32_bf16 v[54:57], v[170:173], v[114:117], v[54:57]
	v_mfma_f32_16x16x32_bf16 v[54:57], v[174:177], v[118:121], v[54:57]
	v_mfma_f32_16x16x32_bf16 v[54:57], v[178:181], v[122:125], v[54:57]
	s_waitcnt lgkmcnt(0)
	v_mfma_f32_16x16x32_bf16 v[58:61], v[200:203], v[110:113], 0
	v_mfma_f32_16x16x32_bf16 v[58:61], v[204:207], v[114:117], v[58:61]
	v_mfma_f32_16x16x32_bf16 v[58:61], v[208:211], v[118:121], v[58:61]
	v_mfma_f32_16x16x32_bf16 v[58:61], v[212:215], v[122:125], v[58:61]
	ds_read_b64_tr_b16 v[94:95], v185 offset:17536
	ds_read_b64_tr_b16 v[96:97], v185 offset:21888
	ds_read_b64_tr_b16 v[98:99], v185 offset:26240
	ds_read_b64_tr_b16 v[100:101], v185 offset:30592
	ds_read_b64_tr_b16 v[102:103], v185 offset:17568
	ds_read_b64_tr_b16 v[104:105], v185 offset:21920
	ds_read_b64_tr_b16 v[106:107], v185 offset:26272
	ds_read_b64_tr_b16 v[108:109], v185 offset:30624
	ds_read_b64_tr_b16 v[110:111], v185 offset:17600
	ds_read_b64_tr_b16 v[112:113], v185 offset:21952
	ds_read_b64_tr_b16 v[114:115], v185 offset:26304
	ds_read_b64_tr_b16 v[116:117], v185 offset:30656
	ds_read_b64_tr_b16 v[118:119], v185 offset:17632
	ds_read_b64_tr_b16 v[120:121], v185 offset:21984
	ds_read_b64_tr_b16 v[122:123], v185 offset:26336
	ds_read_b64_tr_b16 v[124:125], v185 offset:30688
	ds_read_b128 v[166:169], v188 offset:0
	ds_read_b128 v[170:173], v188 offset:64
	ds_read_b128 v[174:177], v188 offset:128
	ds_read_b128 v[178:181], v188 offset:192
	ds_read_b128 v[200:203], v188 offset:256
	ds_read_b128 v[204:207], v188 offset:320
	ds_read_b128 v[208:211], v188 offset:384
	ds_read_b128 v[212:215], v188 offset:448
	v_mfma_f32_16x16x32_bf16 v[2:5], v[62:65], v[126:129], v[2:5]
	v_mfma_f32_16x16x32_bf16 v[2:5], v[66:69], v[130:133], v[2:5]
	v_mfma_f32_16x16x32_bf16 v[6:9], v[70:73], v[126:129], v[6:9]
	v_mfma_f32_16x16x32_bf16 v[6:9], v[74:77], v[130:133], v[6:9]
	v_mfma_f32_16x16x32_bf16 v[10:13], v[78:81], v[126:129], v[10:13]
	v_mfma_f32_16x16x32_bf16 v[10:13], v[82:85], v[130:133], v[10:13]
	v_mfma_f32_16x16x32_bf16 v[14:17], v[86:89], v[126:129], v[14:17]
	v_mfma_f32_16x16x32_bf16 v[14:17], v[90:93], v[130:133], v[14:17]
	v_cndmask_b32_e64 v42, v42, 0, s[40:41]
	v_cndmask_b32_e64 v43, v43, 0, s[42:43]
	v_cndmask_b32_e64 v44, v44, 0, s[44:45]
	v_cndmask_b32_e64 v45, v45, 0, s[46:47]
	v_cndmask_b32_e64 v58, v58, 0, s[40:41]
	v_cndmask_b32_e64 v59, v59, 0, s[42:43]
	v_cndmask_b32_e64 v60, v60, 0, s[44:45]
	v_cndmask_b32_e64 v61, v61, 0, s[46:47]
	v_cvt_pk_bf16_f32 v134, v42, v43
	v_cvt_pk_bf16_f32 v135, v44, v45
	v_mov_b32_e32 v136, 0
	v_mov_b32_e32 v137, 0
	v_cvt_pk_bf16_f32 v138, v46, v47
	v_cvt_pk_bf16_f32 v139, v48, v49
	v_cvt_pk_bf16_f32 v140, v50, v51
	v_cvt_pk_bf16_f32 v141, v52, v53
	v_cvt_pk_bf16_f32 v142, v54, v55
	v_cvt_pk_bf16_f32 v143, v56, v57
	v_cvt_pk_bf16_f32 v144, v58, v59
	v_cvt_pk_bf16_f32 v145, v60, v61
	v_mfma_f32_16x16x32_bf16 v[34:37], v[126:129], v[134:137], v[34:37]
	v_mfma_f32_16x16x32_bf16 v[38:41], v[126:129], v[138:141], v[38:41]
	v_mfma_f32_16x16x32_bf16 v[38:41], v[130:133], v[142:145], v[38:41]
	s_waitcnt lgkmcnt(8)
	v_mfma_f32_16x16x32_bf16 v[18:21], v[94:97], v[126:129], v[18:21]
	v_mfma_f32_16x16x32_bf16 v[18:21], v[98:101], v[130:133], v[18:21]
	v_mfma_f32_16x16x32_bf16 v[22:25], v[102:105], v[126:129], v[22:25]
	v_mfma_f32_16x16x32_bf16 v[22:25], v[106:109], v[130:133], v[22:25]
	v_mfma_f32_16x16x32_bf16 v[26:29], v[110:113], v[126:129], v[26:29]
	v_mfma_f32_16x16x32_bf16 v[26:29], v[114:117], v[130:133], v[26:29]
	v_mfma_f32_16x16x32_bf16 v[30:33], v[118:121], v[126:129], v[30:33]
	v_mfma_f32_16x16x32_bf16 v[30:33], v[122:125], v[130:133], v[30:33]
	s_add_i32 s64, s12, 1
	s_cmp_gt_u32 s64, 35
	s_nop 5
	s_cbranch_scc1 .Lp8_nost_7
	s_waitcnt vmcnt(0)
	ds_write_b128 v189, v[224:227] offset:17408
	ds_write_b128 v189, v[228:231] offset:26112
	ds_write_b128 v190, v[232:235] offset:34816
	s_cmp_lt_u32 s64, 4
	s_cbranch_scc1 .Lp8_stq_8
	ds_write_b128 v189, v[216:219]
	ds_write_b128 v189, v[220:223] offset:8704

.Lp8_ldd_9:
.Lp8_nost_7:
	v_cvt_pk_bf16_f32 v42, v34, v35
	v_cvt_pk_bf16_f32 v43, v36, v37
	global_store_dwordx2 v241, v[42:43], s[8:9]
	v_cvt_pk_bf16_f32 v44, v38, v39
	v_cvt_pk_bf16_f32 v45, v40, v41
	global_store_dwordx2 v241, v[44:45], s[10:11]
	s_waitcnt lgkmcnt(0)
	v_pk_mul_f32 v[2:3], v[2:3], v[166:167]
	v_pk_mul_f32 v[4:5], v[4:5], v[168:169]
	v_pk_mul_f32 v[6:7], v[6:7], v[170:171]
	v_pk_mul_f32 v[8:9], v[8:9], v[172:173]
	v_pk_mul_f32 v[10:11], v[10:11], v[174:175]
	v_pk_mul_f32 v[12:13], v[12:13], v[176:177]
	v_pk_mul_f32 v[14:15], v[14:15], v[178:179]
	v_pk_mul_f32 v[16:17], v[16:17], v[180:181]
	v_pk_mul_f32 v[18:19], v[18:19], v[200:201]
	v_pk_mul_f32 v[20:21], v[20:21], v[202:203]
	v_pk_mul_f32 v[22:23], v[22:23], v[204:205]
	v_pk_mul_f32 v[24:25], v[24:25], v[206:207]
	v_pk_mul_f32 v[26:27], v[26:27], v[208:209]
	v_pk_mul_f32 v[28:29], v[28:29], v[210:211]
	v_pk_mul_f32 v[30:31], v[30:31], v[212:213]
	v_pk_mul_f32 v[32:33], v[32:33], v[214:215]
	s_nop 1
	s_barrier
	s_branch .Lp8_next
.Lp8_lat1:
	s_sub_i32 s48, 3, s12
	s_sub_i32 s49, 39, s12
	s_cmp_lt_u32 s12, 4
	s_cselect_b32 s48, s48, s49
	s_cmp_eq_u32 s31, 0
	s_cselect_b32 s54, s12, s48
	s_lshl_b32 s48, s54, 6
	s_add_i32 s49, s33, s48
	s_add_i32 s48, s34, s48
	s_cmp_lt_u32 s54, 4
	s_cselect_b32 s55, s49, s48
	s_add_i32 s48, s55, 16
	s_add_i32 s49, s55, 32
	s_cmp_eq_u32 s31, 0
	s_cselect_b32 s48, s48, s49
	s_lshl_b32 s48, s48, 11
	s_add_u32 s8, s28, s48
	s_addc_u32 s9, s29, 0
	s_add_i32 s48, s55, 32
	s_add_i32 s49, s55, 16
	s_cmp_eq_u32 s31, 0
	s_cselect_b32 s48, s48, s49
	s_lshl_b32 s48, s48, 11
	s_add_u32 s10, s28, s48
	s_addc_u32 s11, s29, 0
	ds_read_b64 v[62:63], v183 offset:4352
	ds_read_b64 v[64:65], v183 offset:4384
	ds_read_b64 v[66:67], v183 offset:4416
	ds_read_b64 v[68:69], v183 offset:4448
	ds_read_b64 v[70:71], v183 offset:4480
	ds_read_b64 v[72:73], v183 offset:4512
	ds_read_b64 v[74:75], v183 offset:4544
	ds_read_b64 v[76:77], v183 offset:4576
	ds_read_b64 v[78:79], v183 offset:8704
	ds_read_b64 v[80:81], v183 offset:8736
	ds_read_b64 v[82:83], v183 offset:8768
	ds_read_b64 v[84:85], v183 offset:8800
	ds_read_b64 v[86:87], v183 offset:8832
	ds_read_b64 v[88:89], v183 offset:8864
	ds_read_b64 v[90:91], v183 offset:8896
	ds_read_b64 v[92:93], v183 offset:8928
	v_cvt_pk_bf16_f32 v150, v2, v3
	v_cvt_pk_bf16_f32 v151, v4, v5
	v_cvt_pk_bf16_f32 v152, v6, v7
	v_cvt_pk_bf16_f32 v153, v8, v9
	v_cvt_pk_bf16_f32 v154, v10, v11
	v_cvt_pk_bf16_f32 v155, v12, v13
	v_cvt_pk_bf16_f32 v156, v14, v15
	v_cvt_pk_bf16_f32 v157, v16, v17
	v_cvt_pk_bf16_f32 v158, v18, v19
	v_cvt_pk_bf16_f32 v159, v20, v21
	v_cvt_pk_bf16_f32 v160, v22, v23
	v_cvt_pk_bf16_f32 v161, v24, v25
	v_cvt_pk_bf16_f32 v162, v26, v27
	v_cvt_pk_bf16_f32 v163, v28, v29
	v_cvt_pk_bf16_f32 v164, v30, v31
	v_cvt_pk_bf16_f32 v165, v32, v33
	ds_read_b64_tr_b16 v[126:127], v184 offset:34816
	ds_read_b64_tr_b16 v[128:129], v184 offset:37120
	ds_read_b64_tr_b16 v[130:131], v184 offset:39424
	ds_read_b64_tr_b16 v[132:133], v184 offset:41728
	ds_read_b128 v[94:97], v182 offset:4352
	ds_read_b128 v[98:101], v182 offset:4416
	ds_read_b128 v[102:105], v182 offset:4480
	ds_read_b128 v[106:109], v182 offset:4544
	ds_read_b128 v[110:113], v182 offset:8704
	ds_read_b128 v[114:117], v182 offset:8768
	ds_read_b128 v[118:121], v182 offset:8832
	ds_read_b128 v[122:125], v182 offset:8896
	ds_read_b128 v[166:169], v182 offset:17408
	ds_read_b128 v[170:173], v182 offset:17472
	ds_read_b128 v[174:177], v182 offset:17536
	ds_read_b128 v[178:181], v182 offset:17600
	ds_read_b128 v[200:203], v182 offset:21760
	ds_read_b128 v[204:207], v182 offset:21824
	ds_read_b128 v[208:211], v182 offset:21888
	ds_read_b128 v[212:215], v182 offset:21952
	s_waitcnt lgkmcnt(15)
	v_mfma_f32_16x16x32_bf16 v[34:37], v[150:153], v[62:65], 0
	v_mfma_f32_16x16x32_bf16 v[38:41], v[150:153], v[78:81], 0
	v_mfma_f32_16x16x32_bf16 v[34:37], v[154:157], v[66:69], v[34:37]
	v_mfma_f32_16x16x32_bf16 v[38:41], v[154:157], v[82:85], v[38:41]
	v_mfma_f32_16x16x32_bf16 v[34:37], v[158:161], v[70:73], v[34:37]
	v_mfma_f32_16x16x32_bf16 v[38:41], v[158:161], v[86:89], v[38:41]
	v_mfma_f32_16x16x32_bf16 v[34:37], v[162:165], v[74:77], v[34:37]
	v_mfma_f32_16x16x32_bf16 v[38:41], v[162:165], v[90:93], v[38:41]
	ds_read_b64_tr_b16 v[62:63], v185 offset:17408
	ds_read_b64_tr_b16 v[64:65], v185 offset:21760
	ds_read_b64_tr_b16 v[66:67], v185 offset:26112
	ds_read_b64_tr_b16 v[68:69], v185 offset:30464
	ds_read_b64_tr_b16 v[70:71], v185 offset:17440
	ds_read_b64_tr_b16 v[72:73], v185 offset:21792
	ds_read_b64_tr_b16 v[74:75], v185 offset:26144
	ds_read_b64_tr_b16 v[76:77], v185 offset:30496
	ds_read_b64_tr_b16 v[78:79], v185 offset:17472
	ds_read_b64_tr_b16 v[80:81], v185 offset:21824
	ds_read_b64_tr_b16 v[82:83], v185 offset:26176
	ds_read_b64_tr_b16 v[84:85], v185 offset:30528
	ds_read_b64_tr_b16 v[86:87], v185 offset:17504
	ds_read_b64_tr_b16 v[88:89], v185 offset:21856
	ds_read_b64_tr_b16 v[90:91], v185 offset:26208
	ds_read_b64_tr_b16 v[92:93], v185 offset:30560
	s_waitcnt lgkmcnt(15)
	v_mfma_f32_16x16x32_bf16 v[42:45], v[166:169], v[94:97], 0
	v_mfma_f32_16x16x32_bf16 v[50:53], v[166:169], v[110:113], 0
	v_mfma_f32_16x16x32_bf16 v[42:45], v[170:173], v[98:101], v[42:45]
	v_mfma_f32_16x16x32_bf16 v[50:53], v[170:173], v[114:117], v[50:53]
	v_mfma_f32_16x16x32_bf16 v[42:45], v[174:177], v[102:105], v[42:45]
	v_mfma_f32_16x16x32_bf16 v[50:53], v[174:177], v[118:121], v[50:53]
	v_mfma_f32_16x16x32_bf16 v[42:45], v[178:181], v[106:109], v[42:45]
	v_mfma_f32_16x16x32_bf16 v[50:53], v[178:181], v[122:125], v[50:53]
	ds_read_b128 v[166:169], v182 offset:26112
	ds_read_b128 v[170:173], v182 offset:26176
	ds_read_b128 v[174:177], v182 offset:26240
	ds_read_b128 v[178:181], v182 offset:26304
	v_mfma_f32_16x16x32_bf16 v[46:49], v[200:203], v[94:97], 0
	v_mfma_f32_16x16x32_bf16 v[54:57], v[200:203], v[110:113], 0
	v_mfma_f32_16x16x32_bf16 v[46:49], v[204:207], v[98:101], v[46:49]
	v_mfma_f32_16x16x32_bf16 v[54:57], v[204:207], v[114:117], v[54:57]
	v_mfma_f32_16x16x32_bf16 v[46:49], v[208:211], v[102:105], v[46:49]
	v_mfma_f32_16x16x32_bf16 v[54:57], v[208:211], v[118:121], v[54:57]
	v_mfma_f32_16x16x32_bf16 v[46:49], v[212:215], v[106:109], v[46:49]
	v_mfma_f32_16x16x32_bf16 v[54:57], v[212:215], v[122:125], v[54:57]
	s_waitcnt lgkmcnt(0)
	v_mfma_f32_16x16x32_bf16 v[58:61], v[166:169], v[110:113], 0
	v_mfma_f32_16x16x32_bf16 v[58:61], v[170:173], v[114:117], v[58:61]
	v_mfma_f32_16x16x32_bf16 v[58:61], v[174:177], v[118:121], v[58:61]
	v_mfma_f32_16x16x32_bf16 v[58:61], v[178:181], v[122:125], v[58:61]
	ds_read_b64_tr_b16 v[94:95], v185 offset:17536
	ds_read_b64_tr_b16 v[96:97], v185 offset:21888
	ds_read_b64_tr_b16 v[98:99], v185 offset:26240
	ds_read_b64_tr_b16 v[100:101], v185 offset:30592
	ds_read_b64_tr_b16 v[102:103], v185 offset:17568
	ds_read_b64_tr_b16 v[104:105], v185 offset:21920
	ds_read_b64_tr_b16 v[106:107], v185 offset:26272
	ds_read_b64_tr_b16 v[108:109], v185 offset:30624
	ds_read_b64_tr_b16 v[110:111], v185 offset:17600
	ds_read_b64_tr_b16 v[112:113], v185 offset:21952
	ds_read_b64_tr_b16 v[114:115], v185 offset:26304
	ds_read_b64_tr_b16 v[116:117], v185 offset:30656
	ds_read_b64_tr_b16 v[118:119], v185 offset:17632
	ds_read_b64_tr_b16 v[120:121], v185 offset:21984
	ds_read_b64_tr_b16 v[122:123], v185 offset:26336
	ds_read_b64_tr_b16 v[124:125], v185 offset:30688
	ds_read_b128 v[166:169], v188 offset:0
	ds_read_b128 v[170:173], v188 offset:64
	ds_read_b128 v[174:177], v188 offset:128
	ds_read_b128 v[178:181], v188 offset:192
	ds_read_b128 v[200:203], v188 offset:256
	ds_read_b128 v[204:207], v188 offset:320
	ds_read_b128 v[208:211], v188 offset:384
	ds_read_b128 v[212:215], v188 offset:448
	v_mfma_f32_16x16x32_bf16 v[2:5], v[62:65], v[126:129], v[2:5]
	v_mfma_f32_16x16x32_bf16 v[2:5], v[66:69], v[130:133], v[2:5]
	v_mfma_f32_16x16x32_bf16 v[6:9], v[70:73], v[126:129], v[6:9]
	v_mfma_f32_16x16x32_bf16 v[6:9], v[74:77], v[130:133], v[6:9]
	v_mfma_f32_16x16x32_bf16 v[10:13], v[78:81], v[126:129], v[10:13]
	v_mfma_f32_16x16x32_bf16 v[10:13], v[82:85], v[130:133], v[10:13]
	v_mfma_f32_16x16x32_bf16 v[14:17], v[86:89], v[126:129], v[14:17]
	v_mfma_f32_16x16x32_bf16 v[14:17], v[90:93], v[130:133], v[14:17]
	v_cndmask_b32_e64 v46, v46, 0, s[40:41]
	v_cndmask_b32_e64 v47, v47, 0, s[42:43]
	v_cndmask_b32_e64 v48, v48, 0, s[44:45]
	v_cndmask_b32_e64 v49, v49, 0, s[46:47]
	v_cndmask_b32_e64 v58, v58, 0, s[40:41]
	v_cndmask_b32_e64 v59, v59, 0, s[42:43]
	v_cndmask_b32_e64 v60, v60, 0, s[44:45]
	v_cndmask_b32_e64 v61, v61, 0, s[46:47]
	v_cvt_pk_bf16_f32 v134, v42, v43
	v_cvt_pk_bf16_f32 v135, v44, v45
	v_cvt_pk_bf16_f32 v136, v46, v47
	v_cvt_pk_bf16_f32 v137, v48, v49
	v_cvt_pk_bf16_f32 v138, v50, v51
	v_cvt_pk_bf16_f32 v139, v52, v53
	v_cvt_pk_bf16_f32 v140, v54, v55
	v_cvt_pk_bf16_f32 v141, v56, v57
	v_cvt_pk_bf16_f32 v142, v58, v59
	v_cvt_pk_bf16_f32 v143, v60, v61
	v_mov_b32_e32 v144, 0
	v_mov_b32_e32 v145, 0
	v_mfma_f32_16x16x32_bf16 v[34:37], v[126:129], v[134:137], v[34:37]
	v_mfma_f32_16x16x32_bf16 v[38:41], v[126:129], v[138:141], v[38:41]
	v_mfma_f32_16x16x32_bf16 v[38:41], v[130:133], v[142:145], v[38:41]
	s_waitcnt lgkmcnt(8)
	v_mfma_f32_16x16x32_bf16 v[18:21], v[94:97], v[126:129], v[18:21]
	v_mfma_f32_16x16x32_bf16 v[18:21], v[98:101], v[130:133], v[18:21]
	v_mfma_f32_16x16x32_bf16 v[22:25], v[102:105], v[126:129], v[22:25]
	v_mfma_f32_16x16x32_bf16 v[22:25], v[106:109], v[130:133], v[22:25]
	v_mfma_f32_16x16x32_bf16 v[26:29], v[110:113], v[126:129], v[26:29]
	v_mfma_f32_16x16x32_bf16 v[26:29], v[114:117], v[130:133], v[26:29]
	v_mfma_f32_16x16x32_bf16 v[30:33], v[118:121], v[126:129], v[30:33]
	v_mfma_f32_16x16x32_bf16 v[30:33], v[122:125], v[130:133], v[30:33]
	s_add_i32 s64, s12, 1
	s_cmp_gt_u32 s64, 35
	s_nop 5
	s_cbranch_scc1 .Lp8_nost_10
	s_waitcnt vmcnt(0)
	ds_write_b128 v189, v[224:227] offset:17408
	ds_write_b128 v189, v[228:231] offset:26112
	ds_write_b128 v190, v[232:235] offset:34816
	s_cmp_lt_u32 s64, 4
	s_cbranch_scc1 .Lp8_stq_11
	ds_write_b128 v189, v[216:219]
	ds_write_b128 v189, v[220:223] offset:8704

.Lp8_ldd_12:
.Lp8_nost_10:
	v_cvt_pk_bf16_f32 v42, v34, v35
	v_cvt_pk_bf16_f32 v43, v36, v37
	global_store_dwordx2 v241, v[42:43], s[8:9]
	v_cvt_pk_bf16_f32 v44, v38, v39
	v_cvt_pk_bf16_f32 v45, v40, v41
	global_store_dwordx2 v241, v[44:45], s[10:11]
	s_waitcnt lgkmcnt(0)
	v_pk_mul_f32 v[2:3], v[2:3], v[166:167]
	v_pk_mul_f32 v[4:5], v[4:5], v[168:169]
	v_pk_mul_f32 v[6:7], v[6:7], v[170:171]
	v_pk_mul_f32 v[8:9], v[8:9], v[172:173]
	v_pk_mul_f32 v[10:11], v[10:11], v[174:175]
	v_pk_mul_f32 v[12:13], v[12:13], v[176:177]
	v_pk_mul_f32 v[14:15], v[14:15], v[178:179]
	v_pk_mul_f32 v[16:17], v[16:17], v[180:181]
	v_pk_mul_f32 v[18:19], v[18:19], v[200:201]
	v_pk_mul_f32 v[20:21], v[20:21], v[202:203]
	v_pk_mul_f32 v[22:23], v[22:23], v[204:205]
	v_pk_mul_f32 v[24:25], v[24:25], v[206:207]
	v_pk_mul_f32 v[26:27], v[26:27], v[208:209]
	v_pk_mul_f32 v[28:29], v[28:29], v[210:211]
	v_pk_mul_f32 v[30:31], v[30:31], v[212:213]
	v_pk_mul_f32 v[32:33], v[32:33], v[214:215]
	s_nop 1
	s_barrier
.Lp8_next:
	s_add_i32 s12, s12, 1
	s_cmp_lt_u32 s12, 36
	s_cbranch_scc1 .Lp8_step
	s_branch .LBB0_997
